# QKV epilogue: RoPE cos/sin rows of steps 1-3 loaded once per row half (6 contiguous dwordx4/lane), staged in the idle K-stage-1 LDS buffers, read with ds_read_b128 (was 24 scattered global loads per l
# speedup vs baseline: 1.0100x; 1.0068x over previous
; #define LAS __attribute__((address_space(3)))
;   DI void operator()(LAS unsigned char* lds, f32x4 (&acc)[2][2][4][2], int pm, int pn, int wr, int wc, int fr, int fq) const {
;     ...
;     for (int aim = 0; aim < 4; ++aim) {
;       const int ai = aim >> 1, mb = (aim & 1) * 2;
;       f32x4 cs[4][2], sn[4][2];
;       if (type < 2) {
; #pragma unroll
;         for (int m = mb; m < mb + 2; ++m)
; #pragma unroll
;           for (int n = 0; n < 2; ++n) {
;             if (aim == 0) {
;               const int tr = wr * 32 + m * 16 + fr;
;               cs[m][n] = *(const LAS f32x4*)(lds + EQ_CS + tr * EQ_CSS + (8 * fq + 4 * n) * 4);
;               sn[m][n] = *(const LAS f32x4*)(lds + EQ_CS + tr * EQ_CSS + 128 + (8 * fq + 4 * n) * 4);
;             } else {
;               const size_t o = (size_t)(s0 + ai * HALF + m * 16) * 32 + 8 * fq + 4 * n;
;               cs[m][n] = *(const f32x4*)(cosT + o); sn[m][n] = *(const f32x4*)(sinT + o);
;             }
;           }
.LBB0_468:
	v_cndmask_b32_e64 v70, 0, 1, s[36:37]
	v_cmp_ne_u32_e64 s[44:45], 1, v70
	s_andn2_b64 vcc, exec, s[36:37]
	s_cbranch_vccnz .LBB0_470
	v_and_b32_e32 v230, 0xff, v220
	v_lshrrev_b32_e32 v232, 3, v230
	v_and_b32_e32 v230, 7, v230
	v_add3_u32 v214, s18, v228, v232
	v_lshlrev_b32_e32 v214, 7, v214
	v_lshl_add_u32 v214, v230, 4, v214
	v_mov_b32_e32 v215, 0
	v_mul_u32_u24_e32 v251, 0x90, v232
	v_lshl_add_u32 v251, v230, 4, v251
	v_lshrrev_b32_e32 v232, 8, v220
	v_mul_u32_u24_e32 v232, 0x10000, v232
	v_add_u32_e32 v251, v251, v232
	v_add_u32_e32 v251, 0x8000, v251
	v_readlane_b32 s100, v254, 8
	v_readlane_b32 s101, v254, 9
	s_nop 1
	v_lshl_add_u64 v[216:217], s[100:101], 0, v[214:215]
	s_mov_b64 s[100:101], 0x1000
	v_lshl_add_u64 v[216:217], v[216:217], 0, s[100:101]
	global_load_dwordx4 v[198:201], v[216:217], off
	s_mov_b64 s[100:101], 0x3000
	v_lshl_add_u64 v[216:217], v[216:217], 0, s[100:101]
	global_load_dwordx4 v[202:205], v[216:217], off
	s_mov_b64 s[100:101], 0x1000
	v_lshl_add_u64 v[216:217], v[216:217], 0, s[100:101]
	global_load_dwordx4 v[206:209], v[216:217], off
	v_readlane_b32 s100, v254, 10
	v_readlane_b32 s101, v254, 11
	s_nop 1
	v_lshl_add_u64 v[216:217], s[100:101], 0, v[214:215]
	s_mov_b64 s[100:101], 0x1000
	v_lshl_add_u64 v[216:217], v[216:217], 0, s[100:101]
	global_load_dwordx4 v[210:213], v[216:217], off
	s_mov_b64 s[100:101], 0x3000
	v_lshl_add_u64 v[216:217], v[216:217], 0, s[100:101]
	global_load_dwordx4 v[234:237], v[216:217], off
	s_mov_b64 s[100:101], 0x1000
	v_lshl_add_u64 v[216:217], v[216:217], 0, s[100:101]
	global_load_dwordx4 v[238:241], v[216:217], off
	v_mul_u32_u24_e32 v250, 0x90, v219
	v_lshl_add_u32 v250, v218, 5, v250
	v_add_u32_e32 v250, v250, v232
	v_add_u32_e32 v250, 0x8000, v250
	v_lshl_or_b32 v70, v231, 5, v219
	v_mul_lo_u32 v70, v70, s65
	v_readlane_b32 s17, v254, 34
	s_nop 1
	v_add3_u32 v70, s17, v70, v180
	ds_read_b128 v[134:137], v70
	ds_read_b128 v[114:117], v70 offset:16
	ds_read_b128 v[142:145], v70 offset:128
	ds_read_b128 v[130:133], v70 offset:144
	ds_read_b128 v[90:93], v70 offset:4480
	ds_read_b128 v[74:77], v70 offset:4496
	ds_read_b128 v[82:85], v70 offset:4352
	ds_read_b128 v[70:73], v70 offset:4368

; #define LAS __attribute__((address_space(3)))
; DI unsigned cvt_pk(float lo, float hi) { unsigned r; asm("v_cvt_pk_bf16_f32 %0, %1, %2" : "=v"(r) : "v"(lo), "v"(hi)); return r; }
;   DI void operator()(LAS unsigned char* lds, f32x4 (&acc)[2][2][4][2], int pm, int pn, int wr, int wc, int fr, int fq) const {
;     ...
;       if (type < 2) {
; #pragma unroll
;         for (int m = mb; m < mb + 2; ++m)
; #pragma unroll
;           for (int n = 0; n < 2; ++n) {
;             if (aim == 0) {
;               const int tr = wr * 32 + m * 16 + fr;
;               cs[m][n] = *(const LAS f32x4*)(lds + EQ_CS + tr * EQ_CSS + (8 * fq + 4 * n) * 4);
;               sn[m][n] = *(const LAS f32x4*)(lds + EQ_CS + tr * EQ_CSS + 128 + (8 * fq + 4 * n) * 4);
;             } else {
;               const size_t o = (size_t)(s0 + ai * HALF + m * 16) * 32 + 8 * fq + 4 * n;
;               cs[m][n] = *(const f32x4*)(cosT + o); sn[m][n] = *(const f32x4*)(sinT + o);
;             }
;           }
;       }
;       EPI_FENCE;
; #pragma unroll
;       for (int m = mb; m < mb + 2; ++m) {
;         const int s = s0 + ai * HALF + m * 16;
;         f32x4 v[2][2];
; #pragma unroll
;         for (int bj = 0; bj < 2; ++bj)
; #pragma unroll
;           for (int n = 0; n < 2; ++n) v[bj][n] = acc[ai][bj][m][n] * rstd[ai][m];
;         if (type < 2) {
;           float q = 0.f;
; #pragma unroll
;           for (int bj = 0; bj < 2; ++bj)
; #pragma unroll
;             for (int n = 0; n < 2; ++n) q += v[bj][n][0] * v[bj][n][0] + v[bj][n][1] * v[bj][n][1] + v[bj][n][2] * v[bj][n][2] + v[bj][n][3] * v[bj][n][3];
;           q += __shfl_xor(q, 16); q += __shfl_xor(q, 32);
;           float rn = rsqrtf(q * (1.0f / 64.0f) + EPS);
;           if (type == 0) rn *= 0.125f * LOG2E;
; #pragma unroll
;           for (int n = 0; n < 2; ++n) {
;             const f32x4 x1 = v[0][n] * g1[n] * rn, x2 = v[1][n] * g2[n] * rn;
;             v[0][n] = x1 * cs[m][n] - x2 * sn[m][n]; v[1][n] = x2 * cs[m][n] + x1 * sn[m][n];
;           }
;         }
;         bf16_t* rp = base + (size_t)s * 64 + 8 * fq;
; #pragma unroll
;         for (int bj = 0; bj < 2; ++bj) {
;           u32x4 w; w.x = cvt_pk(v[bj][0][0], v[bj][0][1]); w.y = cvt_pk(v[bj][0][2], v[bj][0][3]); w.z = cvt_pk(v[bj][1][0], v[bj][1][1]); w.w = cvt_pk(v[bj][1][2], v[bj][1][3]);
;           *(u32x4*)(rp + bj * 32) = w;
;         }
.LBB0_474:
	v_or_b32_e32 v88, 16, v182
	v_ashrrev_i32_e32 v89, 31, v88
	v_lshlrev_b64 v[88:89], 7, v[88:89]
	v_lshl_add_u64 v[88:89], v[180:181], 0, v[88:89]
	v_cvt_pk_bf16_f32 v96, v98, v99
	v_cvt_pk_bf16_f32 v97, v80, v81
	v_cvt_pk_bf16_f32 v98, v100, v101
	v_cvt_pk_bf16_f32 v99, v68, v69
	global_store_dwordx4 v[88:89], v[96:99], off
	v_cvt_pk_bf16_f32 v94, v94, v95
	v_cvt_pk_bf16_f32 v95, v66, v67
	v_lshlrev_b32_e32 v0, 3, v218
	v_or_b32_e32 v190, 32, v182
	v_cvt_pk_bf16_f32 v96, v86, v87
	v_cvt_pk_bf16_f32 v97, v78, v79
	global_store_dwordx4 v[88:89], v[94:97], off offset:64
	v_or_b32_e32 v188, 48, v182
	s_and_b64 vcc, exec, s[44:45]
	v_ashrrev_i32_e32 v191, 31, v190
	v_lshlrev_b32_e32 v0, 2, v0
	v_ashrrev_i32_e32 v189, 31, v188
	s_cbranch_vccnz .LBB0_476
	v_lshlrev_b64 v[66:67], 7, v[190:191]
	v_readlane_b32 s18, v254, 8
	v_readlane_b32 s20, v254, 10
	v_lshlrev_b64 v[78:79], 7, v[188:189]
	v_or_b32_e32 v66, v66, v0
	v_readlane_b32 s19, v254, 9
	v_readlane_b32 s21, v254, 11
	v_or_b32_e32 v78, v78, v0
	v_lshl_add_u64 v[68:69], s[18:19], 0, v[66:67]
	v_lshl_add_u64 v[66:67], s[20:21], 0, v[66:67]
	v_lshl_add_u64 v[80:81], s[18:19], 0, v[78:79]
	v_lshl_add_u64 v[94:95], s[20:21], 0, v[78:79]
	s_nop 0
	s_nop 0
	s_nop 0
	s_waitcnt vmcnt(4)
	ds_write_b128 v251, v[198:201]
	ds_write_b128 v251, v[202:205] offset:4608
	ds_write_b128 v251, v[206:209] offset:9216
	ds_write_b128 v251, v[210:213] offset:13824
	ds_write_b128 v251, v[234:237] offset:18432
	ds_write_b128 v251, v[238:241] offset:23040
	s_waitcnt lgkmcnt(0)
	s_barrier
	ds_read_b128 v[98:101], v250 offset:16
	ds_read_b128 v[126:129], v250 offset:0
	ds_read_b128 v[122:125], v250 offset:13840
	ds_read_b128 v[138:141], v250 offset:13824
	ds_read_b128 v[66:69], v250 offset:2320
	ds_read_b128 v[86:89], v250 offset:2304
	ds_read_b128 v[78:81], v250 offset:16144
	ds_read_b128 v[94:97], v250 offset:16128
.LBB0_476:
	v_pk_mul_f32 v[168:169], v[168:169], v[186:187] op_sel_hi:[1,0]
	v_pk_mul_f32 v[192:193], v[166:167], v[186:187] op_sel_hi:[1,0]
	v_pk_mul_f32 v[164:165], v[164:165], v[186:187] op_sel_hi:[1,0]
	v_pk_mul_f32 v[194:195], v[162:163], v[186:187] op_sel_hi:[1,0]
	v_pk_mul_f32 v[162:163], v[176:177], v[186:187] op_sel_hi:[1,0]
	v_pk_mul_f32 v[174:175], v[174:175], v[186:187] op_sel_hi:[1,0]
	v_pk_mul_f32 v[166:167], v[172:173], v[186:187] op_sel_hi:[1,0]
	s_and_b64 vcc, exec, s[44:45]
	v_pk_mul_f32 v[170:171], v[170:171], v[186:187] op_sel_hi:[1,0]
	s_cbranch_vccnz .LBB0_478
	v_mov_b32_e32 v176, v193
	v_mov_b32_e32 v177, v195
	v_mov_b32_e32 v172, v192
	v_mov_b32_e32 v173, v194
	v_pk_mul_f32 v[176:177], v[176:177], v[176:177]
	v_mov_b32_e32 v196, v171
	v_pk_fma_f32 v[172:173], v[172:173], v[172:173], v[176:177]
	v_mov_b32_e32 v176, v168
	v_mov_b32_e32 v177, v164
	v_pk_fma_f32 v[172:173], v[176:177], v[176:177], v[172:173]
	v_mov_b32_e32 v176, v169
	v_mov_b32_e32 v177, v165
	v_mov_b32_e32 v197, v175
	v_pk_fma_f32 v[172:173], v[176:177], v[176:177], v[172:173]
	v_mov_b32_e32 v176, v170
	v_mov_b32_e32 v177, v174
	v_pk_mul_f32 v[196:197], v[196:197], v[196:197]
	v_add_f32_e32 v172, v172, v173
	v_pk_fma_f32 v[176:177], v[176:177], v[176:177], v[196:197]
	v_mov_b32_e32 v196, v166
	v_mov_b32_e32 v197, v162
	v_pk_fma_f32 v[176:177], v[196:197], v[196:197], v[176:177]
	v_mov_b32_e32 v196, v167
	v_mov_b32_e32 v197, v163
	v_pk_fma_f32 v[176:177], v[196:197], v[196:197], v[176:177]
	v_xor_b32_e32 v173, 16, v224
	v_add_f32_e32 v172, v177, v172
	v_add_f32_e32 v172, v176, v172
	v_and_b32_e32 v176, 64, v224
	v_add_u32_e32 v176, 64, v176
	v_cmp_lt_i32_e32 vcc, v173, v176
	v_pk_mul_f32 v[168:169], v[168:169], v[16:17]
	v_pk_mul_f32 v[162:163], v[162:163], v[12:13]
	v_cndmask_b32_e32 v173, v224, v173, vcc
	v_lshlrev_b32_e32 v173, 2, v173
	ds_bpermute_b32 v173, v173, v172
	v_pk_mul_f32 v[164:165], v[164:165], v[8:9]
	s_waitcnt lgkmcnt(0)
	v_add_f32_e32 v172, v172, v173
	v_xor_b32_e32 v173, 32, v224
	v_cmp_lt_i32_e32 vcc, v173, v176
	v_pk_mul_f32 v[176:177], v[192:193], v[14:15]
	s_nop 0
	v_cndmask_b32_e32 v173, v224, v173, vcc
	v_lshlrev_b32_e32 v173, 2, v173
	ds_bpermute_b32 v173, v173, v172
	s_waitcnt lgkmcnt(0)
	v_add_f32_e32 v172, v172, v173
	v_fmamk_f32 v172, v172, 0x3c800000, v227
	v_mul_f32_e32 v173, 0x4b800000, v172
	v_cmp_gt_f32_e32 vcc, s16, v172
	s_nop 1
	v_cndmask_b32_e32 v172, v172, v173, vcc
	v_rsq_f32_e32 v172, v172
	s_nop 0
	v_mul_f32_e32 v173, 0x45800000, v172
	v_cndmask_b32_e32 v172, v172, v173, vcc
	v_mul_f32_e32 v173, 0x3e38aa3b, v172
	v_cndmask_b32_e64 v172, v172, v173, s[96:97]
	v_pk_mul_f32 v[196:197], v[168:169], v[172:173] op_sel_hi:[1,0]
	v_pk_mul_f32 v[168:169], v[174:175], v[10:11]
	v_pk_mul_f32 v[162:163], v[162:163], v[172:173] op_sel_hi:[1,0]
	v_pk_mul_f32 v[174:175], v[168:169], v[172:173] op_sel_hi:[1,0]
	v_pk_mul_f32 v[176:177], v[176:177], v[172:173] op_sel_hi:[1,0]
	s_waitcnt lgkmcnt(0)
	v_pk_mul_f32 v[192:193], v[138:139], v[174:175]
	v_pk_mul_f32 v[168:169], v[140:141], v[162:163]
	v_pk_fma_f32 v[192:193], v[126:127], v[176:177], v[192:193] neg_lo:[0,0,1] neg_hi:[0,0,1]
	v_pk_fma_f32 v[168:169], v[128:129], v[196:197], v[168:169] neg_lo:[0,0,1] neg_hi:[0,0,1]
	v_pk_mul_f32 v[176:177], v[138:139], v[176:177]
	v_pk_mul_f32 v[196:197], v[140:141], v[196:197]
	v_pk_fma_f32 v[174:175], v[126:127], v[174:175], v[176:177]
	v_pk_fma_f32 v[162:163], v[128:129], v[162:163], v[196:197]
	v_pk_mul_f32 v[176:177], v[194:195], v[6:7]
	v_pk_mul_f32 v[196:197], v[164:165], v[172:173] op_sel_hi:[1,0]
	v_pk_mul_f32 v[164:165], v[166:167], v[4:5]
	v_pk_mul_f32 v[166:167], v[170:171], v[2:3]
	v_pk_mul_f32 v[176:177], v[176:177], v[172:173] op_sel_hi:[1,0]
	v_pk_mul_f32 v[170:171], v[164:165], v[172:173] op_sel_hi:[1,0]
	v_pk_mul_f32 v[172:173], v[166:167], v[172:173] op_sel_hi:[1,0]
	v_pk_mul_f32 v[164:165], v[124:125], v[170:171]
	v_pk_mul_f32 v[166:167], v[122:123], v[172:173]
	v_pk_fma_f32 v[164:165], v[100:101], v[196:197], v[164:165] neg_lo:[0,0,1] neg_hi:[0,0,1]
	v_pk_fma_f32 v[194:195], v[98:99], v[176:177], v[166:167] neg_lo:[0,0,1] neg_hi:[0,0,1]
	v_pk_mul_f32 v[176:177], v[122:123], v[176:177]
	v_pk_mul_f32 v[166:167], v[124:125], v[196:197]
	s_nop 0
	v_pk_fma_f32 v[166:167], v[100:101], v[170:171], v[166:167]
	v_pk_fma_f32 v[170:171], v[98:99], v[172:173], v[176:177]
; #define LAS __attribute__((address_space(3)))
; DI unsigned cvt_pk(float lo, float hi) { unsigned r; asm("v_cvt_pk_bf16_f32 %0, %1, %2" : "=v"(r) : "v"(lo), "v"(hi)); return r; }
;   DI void operator()(LAS unsigned char* lds, f32x4 (&acc)[2][2][4][2], int pm, int pn, int wr, int wc, int fr, int fq) const {
;     ...
;       if (type < 2) {
; #pragma unroll
;         for (int m = mb; m < mb + 2; ++m)
; #pragma unroll
;           for (int n = 0; n < 2; ++n) {
;             if (aim == 0) {
;               const int tr = wr * 32 + m * 16 + fr;
;               cs[m][n] = *(const LAS f32x4*)(lds + EQ_CS + tr * EQ_CSS + (8 * fq + 4 * n) * 4);
;               sn[m][n] = *(const LAS f32x4*)(lds + EQ_CS + tr * EQ_CSS + 128 + (8 * fq + 4 * n) * 4);
;             } else {
;               const size_t o = (size_t)(s0 + ai * HALF + m * 16) * 32 + 8 * fq + 4 * n;
;               cs[m][n] = *(const f32x4*)(cosT + o); sn[m][n] = *(const f32x4*)(sinT + o);
;             }
;           }
;       }
;       EPI_FENCE;
; #pragma unroll
;       for (int m = mb; m < mb + 2; ++m) {
;         const int s = s0 + ai * HALF + m * 16;
;         f32x4 v[2][2];
; #pragma unroll
;         for (int bj = 0; bj < 2; ++bj)
; #pragma unroll
;           for (int n = 0; n < 2; ++n) v[bj][n] = acc[ai][bj][m][n] * rstd[ai][m];
;         if (type < 2) {
;           float q = 0.f;
; #pragma unroll
;           for (int bj = 0; bj < 2; ++bj)
; #pragma unroll
;             for (int n = 0; n < 2; ++n) q += v[bj][n][0] * v[bj][n][0] + v[bj][n][1] * v[bj][n][1] + v[bj][n][2] * v[bj][n][2] + v[bj][n][3] * v[bj][n][3];
;           q += __shfl_xor(q, 16); q += __shfl_xor(q, 32);
;           float rn = rsqrtf(q * (1.0f / 64.0f) + EPS);
;           if (type == 0) rn *= 0.125f * LOG2E;
; #pragma unroll
;           for (int n = 0; n < 2; ++n) {
;             const f32x4 x1 = v[0][n] * g1[n] * rn, x2 = v[1][n] * g2[n] * rn;
;             v[0][n] = x1 * cs[m][n] - x2 * sn[m][n]; v[1][n] = x2 * cs[m][n] + x1 * sn[m][n];
;           }
;         }
;         bf16_t* rp = base + (size_t)s * 64 + 8 * fq;
; #pragma unroll
;         for (int bj = 0; bj < 2; ++bj) {
;           u32x4 w; w.x = cvt_pk(v[bj][0][0], v[bj][0][1]); w.y = cvt_pk(v[bj][0][2], v[bj][0][3]); w.z = cvt_pk(v[bj][1][0], v[bj][1][1]); w.w = cvt_pk(v[bj][1][2], v[bj][1][3]);
;           *(u32x4*)(rp + bj * 32) = w;
;         }
.LBB0_478:
	v_lshlrev_b64 v[172:173], 7, v[190:191]
	v_cvt_pk_bf16_f32 v170, v170, v171
	v_cvt_pk_bf16_f32 v171, v166, v167
	v_mov_b32_e32 v166, v187
	v_lshl_add_u64 v[172:173], v[180:181], 0, v[172:173]
	v_cvt_pk_bf16_f32 v190, v192, v193
	v_cvt_pk_bf16_f32 v191, v168, v169
	v_cvt_pk_bf16_f32 v193, v164, v165
	v_cvt_pk_bf16_f32 v169, v162, v163
	v_pk_mul_f32 v[152:153], v[152:153], v[166:167] op_sel_hi:[1,0]
	v_pk_mul_f32 v[162:163], v[150:151], v[166:167] op_sel_hi:[1,0]
	v_pk_mul_f32 v[148:149], v[148:149], v[166:167] op_sel_hi:[1,0]
	v_pk_mul_f32 v[164:165], v[146:147], v[166:167] op_sel_hi:[1,0]
	v_pk_mul_f32 v[146:147], v[160:161], v[166:167] op_sel_hi:[1,0]
	v_pk_mul_f32 v[158:159], v[158:159], v[166:167] op_sel_hi:[1,0]
	v_pk_mul_f32 v[150:151], v[156:157], v[166:167] op_sel_hi:[1,0]
	s_and_b64 vcc, exec, s[44:45]
	v_pk_mul_f32 v[154:155], v[154:155], v[166:167] op_sel_hi:[1,0]
	v_cvt_pk_bf16_f32 v192, v194, v195
	global_store_dwordx4 v[172:173], v[190:193], off
	v_cvt_pk_bf16_f32 v168, v174, v175
	global_store_dwordx4 v[172:173], v[168:171], off offset:64
	s_cbranch_vccnz .LBB0_480
	v_mov_b32_e32 v160, v163
	v_mov_b32_e32 v161, v165
	v_mov_b32_e32 v156, v162
	v_mov_b32_e32 v157, v164
	v_pk_mul_f32 v[160:161], v[160:161], v[160:161]
	v_mov_b32_e32 v166, v155
	v_pk_fma_f32 v[156:157], v[156:157], v[156:157], v[160:161]
	v_mov_b32_e32 v160, v152
	v_mov_b32_e32 v161, v148
	v_pk_fma_f32 v[156:157], v[160:161], v[160:161], v[156:157]
	v_mov_b32_e32 v160, v153
	v_mov_b32_e32 v161, v149
	v_mov_b32_e32 v167, v159
	v_pk_fma_f32 v[156:157], v[160:161], v[160:161], v[156:157]
	v_mov_b32_e32 v160, v154
	v_mov_b32_e32 v161, v158
	v_pk_mul_f32 v[166:167], v[166:167], v[166:167]
	v_add_f32_e32 v156, v156, v157
	v_pk_fma_f32 v[160:161], v[160:161], v[160:161], v[166:167]
	v_mov_b32_e32 v166, v150
	v_mov_b32_e32 v167, v146
	v_pk_fma_f32 v[160:161], v[166:167], v[166:167], v[160:161]
	v_mov_b32_e32 v166, v151
	v_mov_b32_e32 v167, v147
	v_pk_fma_f32 v[160:161], v[166:167], v[166:167], v[160:161]
	v_xor_b32_e32 v157, 16, v224
	v_add_f32_e32 v156, v161, v156
	v_add_f32_e32 v156, v160, v156
	v_and_b32_e32 v160, 64, v224
	v_add_u32_e32 v160, 64, v160
	v_cmp_lt_i32_e32 vcc, v157, v160
	v_pk_mul_f32 v[152:153], v[152:153], v[16:17]
	v_pk_mul_f32 v[146:147], v[146:147], v[12:13]
	v_cndmask_b32_e32 v157, v224, v157, vcc
	v_lshlrev_b32_e32 v157, 2, v157
	ds_bpermute_b32 v157, v157, v156
	v_pk_mul_f32 v[148:149], v[148:149], v[8:9]
	s_waitcnt lgkmcnt(0)
	v_add_f32_e32 v156, v156, v157
	v_xor_b32_e32 v157, 32, v224
	v_cmp_lt_i32_e32 vcc, v157, v160
	v_pk_mul_f32 v[160:161], v[162:163], v[14:15]
	s_nop 0
	v_cndmask_b32_e32 v157, v224, v157, vcc
	v_lshlrev_b32_e32 v157, 2, v157
	ds_bpermute_b32 v157, v157, v156
	s_waitcnt lgkmcnt(0)
	v_add_f32_e32 v156, v156, v157
	v_fmamk_f32 v156, v156, 0x3c800000, v227
	v_mul_f32_e32 v157, 0x4b800000, v156
	v_cmp_gt_f32_e32 vcc, s16, v156
	s_nop 1
	v_cndmask_b32_e32 v156, v156, v157, vcc
	v_rsq_f32_e32 v156, v156
	s_nop 0
	v_mul_f32_e32 v157, 0x45800000, v156
	v_cndmask_b32_e32 v156, v156, v157, vcc
	v_mul_f32_e32 v157, 0x3e38aa3b, v156
	v_cndmask_b32_e64 v156, v156, v157, s[96:97]
	v_pk_mul_f32 v[166:167], v[152:153], v[156:157] op_sel_hi:[1,0]
	v_pk_mul_f32 v[152:153], v[158:159], v[10:11]
	v_pk_mul_f32 v[146:147], v[146:147], v[156:157] op_sel_hi:[1,0]
	v_pk_mul_f32 v[158:159], v[152:153], v[156:157] op_sel_hi:[1,0]
	v_pk_mul_f32 v[160:161], v[160:161], v[156:157] op_sel_hi:[1,0]
	s_waitcnt lgkmcnt(0)
	v_pk_mul_f32 v[162:163], v[94:95], v[158:159]
	v_pk_mul_f32 v[152:153], v[96:97], v[146:147]
	v_pk_fma_f32 v[162:163], v[86:87], v[160:161], v[162:163] neg_lo:[0,0,1] neg_hi:[0,0,1]
	v_pk_fma_f32 v[152:153], v[88:89], v[166:167], v[152:153] neg_lo:[0,0,1] neg_hi:[0,0,1]
	v_pk_mul_f32 v[160:161], v[94:95], v[160:161]
	v_pk_mul_f32 v[166:167], v[96:97], v[166:167]
	v_pk_fma_f32 v[158:159], v[86:87], v[158:159], v[160:161]
	v_pk_fma_f32 v[146:147], v[88:89], v[146:147], v[166:167]
	v_pk_mul_f32 v[160:161], v[164:165], v[6:7]
	v_pk_mul_f32 v[166:167], v[148:149], v[156:157] op_sel_hi:[1,0]
	v_pk_mul_f32 v[148:149], v[150:151], v[4:5]
	v_pk_mul_f32 v[150:151], v[154:155], v[2:3]
	v_pk_mul_f32 v[160:161], v[160:161], v[156:157] op_sel_hi:[1,0]
	v_pk_mul_f32 v[154:155], v[148:149], v[156:157] op_sel_hi:[1,0]
	v_pk_mul_f32 v[156:157], v[150:151], v[156:157] op_sel_hi:[1,0]
	v_pk_mul_f32 v[148:149], v[80:81], v[154:155]
	v_pk_mul_f32 v[150:151], v[78:79], v[156:157]
	v_pk_fma_f32 v[148:149], v[68:69], v[166:167], v[148:149] neg_lo:[0,0,1] neg_hi:[0,0,1]
	v_pk_fma_f32 v[164:165], v[66:67], v[160:161], v[150:151] neg_lo:[0,0,1] neg_hi:[0,0,1]
	v_pk_mul_f32 v[160:161], v[78:79], v[160:161]
	v_pk_mul_f32 v[150:151], v[80:81], v[166:167]
	s_nop 0
	v_pk_fma_f32 v[150:151], v[68:69], v[154:155], v[150:151]
	v_pk_fma_f32 v[154:155], v[66:67], v[156:157], v[160:161]
.LBB0_480:
	v_lshlrev_b64 v[156:157], 7, v[188:189]
	v_lshl_add_u64 v[156:157], v[180:181], 0, v[156:157]
	v_cvt_pk_bf16_f32 v160, v162, v163
	v_cvt_pk_bf16_f32 v161, v152, v153
	v_cvt_pk_bf16_f32 v162, v164, v165
	v_cvt_pk_bf16_f32 v163, v148, v149
	global_store_dwordx4 v[156:157], v[160:163], off
	v_cvt_pk_bf16_f32 v152, v158, v159
	v_cvt_pk_bf16_f32 v153, v146, v147
	v_cvt_pk_bf16_f32 v154, v154, v155
	v_cvt_pk_bf16_f32 v155, v150, v151
	global_store_dwordx4 v[156:157], v[152:155], off offset:64
	v_add_u32_e32 v146, 0x80, v182
	s_and_b64 vcc, exec, s[44:45]
	v_ashrrev_i32_e32 v147, 31, v146
	s_cbranch_vccnz .LBB0_482
	v_lshlrev_b64 v[70:71], 7, v[146:147]
	v_readlane_b32 s18, v254, 8
	v_readlane_b32 s20, v254, 10
	v_or_b32_e32 v70, v70, v0
	v_readlane_b32 s19, v254, 9
	v_readlane_b32 s21, v254, 11
	s_mov_b64 s[28:29], 0x4800
	v_lshl_add_u64 v[72:73], s[18:19], 0, v[70:71]
	v_lshl_add_u64 v[70:71], s[20:21], 0, v[70:71]
	v_lshlrev_b64 v[70:71], 7, v[182:183]
	v_or_b32_e32 v70, v70, v0
	v_lshl_add_u64 v[74:75], v[70:71], 0, s[28:29]
	v_lshl_add_u64 v[76:77], s[18:19], 0, v[74:75]
	v_lshl_add_u64 v[90:91], s[20:21], 0, v[74:75]
	s_nop 0
	s_nop 0
	ds_read_b128 v[114:117], v250 offset:4624
	ds_read_b128 v[134:137], v250 offset:4608
	ds_read_b128 v[130:133], v250 offset:18448
	ds_read_b128 v[142:145], v250 offset:18432
	ds_read_b128 v[70:73], v250 offset:6928
	ds_read_b128 v[82:85], v250 offset:6912
	ds_read_b128 v[74:77], v250 offset:20752
	ds_read_b128 v[90:93], v250 offset:20736
;   DI void operator()(LAS unsigned char* lds, f32x4 (&acc)[2][2][4][2], int pm, int pn, int wr, int wc, int fr, int fq) const {
;     ...
;       for (int m = mb; m < mb + 2; ++m) {
;         const int s = s0 + ai * HALF + m * 16;
;         f32x4 v[2][2];
; #pragma unroll
;         for (int bj = 0; bj < 2; ++bj)
; #pragma unroll
;           for (int n = 0; n < 2; ++n) v[bj][n] = acc[ai][bj][m][n] * rstd[ai][m];
;         if (type < 2) {
;           float q = 0.f;
; #pragma unroll
;           for (int bj = 0; bj < 2; ++bj)
; #pragma unroll
;             for (int n = 0; n < 2; ++n) q += v[bj][n][0] * v[bj][n][0] + v[bj][n][1] * v[bj][n][1] + v[bj][n][2] * v[bj][n][2] + v[bj][n][3] * v[bj][n][3];
;           q += __shfl_xor(q, 16); q += __shfl_xor(q, 32);
;           float rn = rsqrtf(q * (1.0f / 64.0f) + EPS);
;           if (type == 0) rn *= 0.125f * LOG2E;
; #pragma unroll
;           for (int n = 0; n < 2; ++n) {
;             const f32x4 x1 = v[0][n] * g1[n] * rn, x2 = v[1][n] * g2[n] * rn;
;             v[0][n] = x1 * cs[m][n] - x2 * sn[m][n]; v[1][n] = x2 * cs[m][n] + x1 * sn[m][n];
;           }
.LBB0_482:
	v_pk_mul_f32 v[112:113], v[112:113], v[184:185] op_sel_hi:[1,0]
	v_pk_mul_f32 v[110:111], v[110:111], v[184:185] op_sel_hi:[1,0]
	v_pk_mul_f32 v[108:109], v[108:109], v[184:185] op_sel_hi:[1,0]
	v_pk_mul_f32 v[148:149], v[106:107], v[184:185] op_sel_hi:[1,0]
	v_pk_mul_f32 v[106:107], v[120:121], v[184:185] op_sel_hi:[1,0]
	v_pk_mul_f32 v[118:119], v[118:119], v[184:185] op_sel_hi:[1,0]
	v_pk_mul_f32 v[104:105], v[104:105], v[184:185] op_sel_hi:[1,0]
	s_and_b64 vcc, exec, s[44:45]
	v_pk_mul_f32 v[102:103], v[102:103], v[184:185] op_sel_hi:[1,0]
	s_cbranch_vccnz .LBB0_484
	v_mov_b32_e32 v150, v111
	v_mov_b32_e32 v151, v149
	v_mov_b32_e32 v120, v110
	v_mov_b32_e32 v121, v148
	v_pk_mul_f32 v[150:151], v[150:151], v[150:151]
	v_mov_b32_e32 v152, v103
	v_pk_fma_f32 v[120:121], v[120:121], v[120:121], v[150:151]
	v_mov_b32_e32 v150, v112
	v_mov_b32_e32 v151, v108
	v_pk_fma_f32 v[120:121], v[150:151], v[150:151], v[120:121]
	v_mov_b32_e32 v150, v113
	v_mov_b32_e32 v151, v109
	v_mov_b32_e32 v153, v119
	v_pk_fma_f32 v[120:121], v[150:151], v[150:151], v[120:121]
	v_mov_b32_e32 v150, v102
	v_mov_b32_e32 v151, v118
	v_pk_mul_f32 v[152:153], v[152:153], v[152:153]
	v_add_f32_e32 v120, v120, v121
	v_pk_fma_f32 v[150:151], v[150:151], v[150:151], v[152:153]
	v_mov_b32_e32 v152, v104
	v_mov_b32_e32 v153, v106
	v_pk_fma_f32 v[150:151], v[152:153], v[152:153], v[150:151]
	v_mov_b32_e32 v152, v105
	v_mov_b32_e32 v153, v107
	v_pk_fma_f32 v[150:151], v[152:153], v[152:153], v[150:151]
	v_xor_b32_e32 v121, 16, v224
	v_add_f32_e32 v120, v151, v120
	v_add_f32_e32 v120, v150, v120
	v_and_b32_e32 v150, 64, v224
	v_add_u32_e32 v150, 64, v150
	v_cmp_lt_i32_e32 vcc, v121, v150
	v_pk_mul_f32 v[110:111], v[110:111], v[14:15]
	v_pk_mul_f32 v[112:113], v[112:113], v[16:17]
	v_cndmask_b32_e32 v121, v224, v121, vcc
	v_lshlrev_b32_e32 v121, 2, v121
	ds_bpermute_b32 v121, v121, v120
	v_pk_mul_f32 v[106:107], v[106:107], v[12:13]
	v_pk_mul_f32 v[102:103], v[102:103], v[2:3]
	v_pk_mul_f32 v[108:109], v[108:109], v[8:9]
	v_pk_mul_f32 v[104:105], v[104:105], v[4:5]
	s_waitcnt lgkmcnt(0)
	v_add_f32_e32 v120, v120, v121
	v_xor_b32_e32 v121, 32, v224
	v_cmp_lt_i32_e32 vcc, v121, v150
	s_nop 1
	v_cndmask_b32_e32 v121, v224, v121, vcc
	v_lshlrev_b32_e32 v121, 2, v121
	ds_bpermute_b32 v121, v121, v120
	s_waitcnt lgkmcnt(0)
	v_add_f32_e32 v120, v120, v121
	v_fmamk_f32 v120, v120, 0x3c800000, v227
	v_mul_f32_e32 v121, 0x4b800000, v120
	v_cmp_gt_f32_e32 vcc, s16, v120
	s_nop 1
	v_cndmask_b32_e32 v120, v120, v121, vcc
	v_rsq_f32_e32 v120, v120
	s_nop 0
	v_mul_f32_e32 v121, 0x45800000, v120
	v_cndmask_b32_e32 v120, v120, v121, vcc
	v_mul_f32_e32 v121, 0x3e38aa3b, v120
	v_cndmask_b32_e64 v120, v120, v121, s[96:97]
	v_pk_mul_f32 v[150:151], v[110:111], v[120:121] op_sel_hi:[1,0]
	v_pk_mul_f32 v[110:111], v[118:119], v[10:11]
	v_pk_mul_f32 v[152:153], v[112:113], v[120:121] op_sel_hi:[1,0]
	v_pk_mul_f32 v[118:119], v[110:111], v[120:121] op_sel_hi:[1,0]
	v_pk_mul_f32 v[106:107], v[106:107], v[120:121] op_sel_hi:[1,0]
	s_waitcnt lgkmcnt(0)
	v_pk_mul_f32 v[110:111], v[142:143], v[118:119]
	v_pk_mul_f32 v[142:143], v[142:143], v[150:151]
	v_pk_mul_f32 v[112:113], v[144:145], v[106:107]
	v_pk_fma_f32 v[110:111], v[134:135], v[150:151], v[110:111] neg_lo:[0,0,1] neg_hi:[0,0,1]
	v_pk_mul_f32 v[144:145], v[144:145], v[152:153]
	v_pk_fma_f32 v[118:119], v[134:135], v[118:119], v[142:143]
	v_pk_mul_f32 v[134:135], v[148:149], v[6:7]
	v_pk_mul_f32 v[102:103], v[102:103], v[120:121] op_sel_hi:[1,0]
	v_pk_fma_f32 v[112:113], v[136:137], v[152:153], v[112:113] neg_lo:[0,0,1] neg_hi:[0,0,1]
	v_pk_fma_f32 v[106:107], v[136:137], v[106:107], v[144:145]
	v_pk_mul_f32 v[134:135], v[134:135], v[120:121] op_sel_hi:[1,0]
	v_pk_mul_f32 v[136:137], v[108:109], v[120:121] op_sel_hi:[1,0]
	v_pk_mul_f32 v[104:105], v[104:105], v[120:121] op_sel_hi:[1,0]
	v_pk_mul_f32 v[120:121], v[130:131], v[102:103]
	v_pk_mul_f32 v[108:109], v[132:133], v[104:105]
	v_pk_fma_f32 v[148:149], v[114:115], v[134:135], v[120:121] neg_lo:[0,0,1] neg_hi:[0,0,1]
	v_pk_mul_f32 v[120:121], v[130:131], v[134:135]
	v_pk_mul_f32 v[130:131], v[132:133], v[136:137]
	v_pk_fma_f32 v[108:109], v[116:117], v[136:137], v[108:109] neg_lo:[0,0,1] neg_hi:[0,0,1]
	v_pk_fma_f32 v[104:105], v[116:117], v[104:105], v[130:131]
	v_pk_fma_f32 v[102:103], v[114:115], v[102:103], v[120:121]
; #define LAS __attribute__((address_space(3)))
; DI unsigned cvt_pk(float lo, float hi) { unsigned r; asm("v_cvt_pk_bf16_f32 %0, %1, %2" : "=v"(r) : "v"(lo), "v"(hi)); return r; }
;   DI void operator()(LAS unsigned char* lds, f32x4 (&acc)[2][2][4][2], int pm, int pn, int wr, int wc, int fr, int fq) const {
;     ...
;       if (type < 2) {
; #pragma unroll
;         for (int m = mb; m < mb + 2; ++m)
; #pragma unroll
;           for (int n = 0; n < 2; ++n) {
;             if (aim == 0) {
;               const int tr = wr * 32 + m * 16 + fr;
;               cs[m][n] = *(const LAS f32x4*)(lds + EQ_CS + tr * EQ_CSS + (8 * fq + 4 * n) * 4);
;               sn[m][n] = *(const LAS f32x4*)(lds + EQ_CS + tr * EQ_CSS + 128 + (8 * fq + 4 * n) * 4);
;             } else {
;               const size_t o = (size_t)(s0 + ai * HALF + m * 16) * 32 + 8 * fq + 4 * n;
;               cs[m][n] = *(const f32x4*)(cosT + o); sn[m][n] = *(const f32x4*)(sinT + o);
;             }
;           }
;       }
;       EPI_FENCE;
; #pragma unroll
;       for (int m = mb; m < mb + 2; ++m) {
;         const int s = s0 + ai * HALF + m * 16;
;         f32x4 v[2][2];
; #pragma unroll
;         for (int bj = 0; bj < 2; ++bj)
; #pragma unroll
;           for (int n = 0; n < 2; ++n) v[bj][n] = acc[ai][bj][m][n] * rstd[ai][m];
;         if (type < 2) {
;           float q = 0.f;
; #pragma unroll
;           for (int bj = 0; bj < 2; ++bj)
; #pragma unroll
;             for (int n = 0; n < 2; ++n) q += v[bj][n][0] * v[bj][n][0] + v[bj][n][1] * v[bj][n][1] + v[bj][n][2] * v[bj][n][2] + v[bj][n][3] * v[bj][n][3];
;           q += __shfl_xor(q, 16); q += __shfl_xor(q, 32);
;           float rn = rsqrtf(q * (1.0f / 64.0f) + EPS);
;           if (type == 0) rn *= 0.125f * LOG2E;
; #pragma unroll
;           for (int n = 0; n < 2; ++n) {
;             const f32x4 x1 = v[0][n] * g1[n] * rn, x2 = v[1][n] * g2[n] * rn;
;             v[0][n] = x1 * cs[m][n] - x2 * sn[m][n]; v[1][n] = x2 * cs[m][n] + x1 * sn[m][n];
;           }
;         }
;         bf16_t* rp = base + (size_t)s * 64 + 8 * fq;
; #pragma unroll
;         for (int bj = 0; bj < 2; ++bj) {
;           u32x4 w; w.x = cvt_pk(v[bj][0][0], v[bj][0][1]); w.y = cvt_pk(v[bj][0][2], v[bj][0][3]); w.z = cvt_pk(v[bj][1][0], v[bj][1][1]); w.w = cvt_pk(v[bj][1][2], v[bj][1][3]);
;           *(u32x4*)(rp + bj * 32) = w;
;         }
.LBB0_484:
	s_waitcnt lgkmcnt(0)
	v_lshlrev_b64 v[114:115], 7, v[146:147]
	v_lshl_add_u64 v[114:115], v[180:181], 0, v[114:115]
	v_cvt_pk_bf16_f32 v110, v110, v111
	v_cvt_pk_bf16_f32 v111, v112, v113
	v_cvt_pk_bf16_f32 v113, v108, v109
	v_cvt_pk_bf16_f32 v109, v106, v107
	v_mov_b32_e32 v106, v185
	v_cvt_pk_bf16_f32 v112, v148, v149
	global_store_dwordx4 v[114:115], v[110:113], off
	v_pk_mul_f32 v[60:61], v[60:61], v[106:107] op_sel_hi:[1,0]
	v_pk_mul_f32 v[52:53], v[52:53], v[106:107] op_sel_hi:[1,0]
	v_cvt_pk_bf16_f32 v110, v102, v103
	v_cvt_pk_bf16_f32 v111, v104, v105
	v_pk_mul_f32 v[102:103], v[58:59], v[106:107] op_sel_hi:[1,0]
	v_pk_mul_f32 v[58:59], v[56:57], v[106:107] op_sel_hi:[1,0]
	v_pk_mul_f32 v[104:105], v[54:55], v[106:107] op_sel_hi:[1,0]
	v_pk_mul_f32 v[54:55], v[64:65], v[106:107] op_sel_hi:[1,0]
	v_pk_mul_f32 v[56:57], v[62:63], v[106:107] op_sel_hi:[1,0]
	s_and_b64 vcc, exec, s[44:45]
	v_pk_mul_f32 v[50:51], v[50:51], v[106:107] op_sel_hi:[1,0]
	v_cvt_pk_bf16_f32 v108, v118, v119
	global_store_dwordx4 v[114:115], v[108:111], off offset:64
	s_cbranch_vccnz .LBB0_486
	v_mov_b32_e32 v64, v103
	v_mov_b32_e32 v65, v105
	v_mov_b32_e32 v62, v102
	v_mov_b32_e32 v63, v104
	v_pk_mul_f32 v[64:65], v[64:65], v[64:65]
	v_mov_b32_e32 v106, v51
	v_pk_fma_f32 v[62:63], v[62:63], v[62:63], v[64:65]
	v_mov_b32_e32 v64, v60
	v_mov_b32_e32 v65, v58
	v_pk_fma_f32 v[62:63], v[64:65], v[64:65], v[62:63]
	v_mov_b32_e32 v64, v61
	v_mov_b32_e32 v65, v59
	v_mov_b32_e32 v107, v57
	v_pk_fma_f32 v[62:63], v[64:65], v[64:65], v[62:63]
	v_mov_b32_e32 v64, v50
	v_mov_b32_e32 v65, v56
	v_pk_mul_f32 v[106:107], v[106:107], v[106:107]
	v_add_f32_e32 v62, v62, v63
	v_pk_fma_f32 v[64:65], v[64:65], v[64:65], v[106:107]
	v_mov_b32_e32 v106, v52
	v_mov_b32_e32 v107, v54
	v_pk_fma_f32 v[64:65], v[106:107], v[106:107], v[64:65]
	v_mov_b32_e32 v106, v53
	v_mov_b32_e32 v107, v55
	v_pk_fma_f32 v[64:65], v[106:107], v[106:107], v[64:65]
	v_xor_b32_e32 v63, 16, v224
	v_add_f32_e32 v62, v65, v62
	v_add_f32_e32 v62, v64, v62
	v_and_b32_e32 v64, 64, v224
	v_add_u32_e32 v64, 64, v64
	v_cmp_lt_i32_e32 vcc, v63, v64
	v_pk_mul_f32 v[56:57], v[56:57], v[10:11]
	v_pk_mul_f32 v[50:51], v[50:51], v[2:3]
	v_cndmask_b32_e32 v63, v224, v63, vcc
	v_lshlrev_b32_e32 v63, 2, v63
	ds_bpermute_b32 v63, v63, v62
	v_pk_mul_f32 v[60:61], v[60:61], v[16:17]
	v_pk_mul_f32 v[54:55], v[54:55], v[12:13]
	v_pk_mul_f32 v[58:59], v[58:59], v[8:9]
	v_pk_mul_f32 v[52:53], v[52:53], v[4:5]
	s_waitcnt lgkmcnt(0)
	v_add_f32_e32 v62, v62, v63
	v_xor_b32_e32 v63, 32, v224
	v_cmp_lt_i32_e32 vcc, v63, v64
	v_pk_mul_f32 v[64:65], v[102:103], v[14:15]
	s_nop 0
	v_cndmask_b32_e32 v63, v224, v63, vcc
	v_lshlrev_b32_e32 v63, 2, v63
	ds_bpermute_b32 v63, v63, v62
	s_waitcnt lgkmcnt(0)
	v_add_f32_e32 v62, v62, v63
	v_fmamk_f32 v62, v62, 0x3c800000, v227
	v_mul_f32_e32 v63, 0x4b800000, v62
	v_cmp_gt_f32_e32 vcc, s16, v62
	s_nop 1
	v_cndmask_b32_e32 v62, v62, v63, vcc
	v_rsq_f32_e32 v62, v62
	s_nop 0
	v_mul_f32_e32 v63, 0x45800000, v62
	v_cndmask_b32_e32 v62, v62, v63, vcc
	v_mul_f32_e32 v63, 0x3e38aa3b, v62
	v_cndmask_b32_e64 v62, v62, v63, s[96:97]
	v_pk_mul_f32 v[56:57], v[56:57], v[62:63] op_sel_hi:[1,0]
	v_pk_mul_f32 v[64:65], v[64:65], v[62:63] op_sel_hi:[1,0]
	v_pk_mul_f32 v[102:103], v[90:91], v[56:57]
	v_pk_mul_f32 v[50:51], v[50:51], v[62:63] op_sel_hi:[1,0]
	v_pk_fma_f32 v[102:103], v[82:83], v[64:65], v[102:103] neg_lo:[0,0,1] neg_hi:[0,0,1]
	v_pk_mul_f32 v[64:65], v[90:91], v[64:65]
	v_pk_mul_f32 v[106:107], v[60:61], v[62:63] op_sel_hi:[1,0]
	v_pk_fma_f32 v[56:57], v[82:83], v[56:57], v[64:65]
	v_pk_mul_f32 v[64:65], v[104:105], v[6:7]
	v_pk_mul_f32 v[54:55], v[54:55], v[62:63] op_sel_hi:[1,0]
	v_pk_mul_f32 v[64:65], v[64:65], v[62:63] op_sel_hi:[1,0]
	v_pk_mul_f32 v[82:83], v[58:59], v[62:63] op_sel_hi:[1,0]
	v_pk_mul_f32 v[52:53], v[52:53], v[62:63] op_sel_hi:[1,0]
	v_pk_mul_f32 v[62:63], v[74:75], v[50:51]
	v_pk_mul_f32 v[60:61], v[92:93], v[54:55]
	v_pk_mul_f32 v[90:91], v[92:93], v[106:107]
	v_pk_mul_f32 v[58:59], v[76:77], v[52:53]
	v_pk_fma_f32 v[104:105], v[70:71], v[64:65], v[62:63] neg_lo:[0,0,1] neg_hi:[0,0,1]
	v_pk_mul_f32 v[62:63], v[74:75], v[64:65]
	v_pk_mul_f32 v[64:65], v[76:77], v[82:83]
	v_pk_fma_f32 v[60:61], v[84:85], v[106:107], v[60:61] neg_lo:[0,0,1] neg_hi:[0,0,1]
	v_pk_fma_f32 v[54:55], v[84:85], v[54:55], v[90:91]
	v_pk_fma_f32 v[58:59], v[72:73], v[82:83], v[58:59] neg_lo:[0,0,1] neg_hi:[0,0,1]
	v_pk_fma_f32 v[52:53], v[72:73], v[52:53], v[64:65]
	v_pk_fma_f32 v[50:51], v[70:71], v[50:51], v[62:63]
.LBB0_486:
	v_lshlrev_b64 v[62:63], 7, v[182:183]
	v_lshl_add_u64 v[64:65], v[180:181], 0, v[62:63]
	s_mov_b64 s[18:19], 0x4800
	v_lshl_add_u64 v[74:75], v[64:65], 0, s[18:19]
	s_movk_i32 s18, 0x4000
	v_cvt_pk_bf16_f32 v73, v58, v59
	v_add_co_u32_e32 v58, vcc, s18, v64
	v_cvt_pk_bf16_f32 v70, v102, v103
	v_cvt_pk_bf16_f32 v71, v60, v61
	v_cvt_pk_bf16_f32 v72, v104, v105
	v_cvt_pk_bf16_f32 v56, v56, v57
	s_nop 1
	v_addc_co_u32_e32 v59, vcc, 0, v65, vcc
	global_store_dwordx4 v[58:59], v[70:73], off offset:2048
	v_cvt_pk_bf16_f32 v57, v54, v55
	v_cvt_pk_bf16_f32 v58, v50, v51
	v_cvt_pk_bf16_f32 v59, v52, v53
	global_store_dwordx4 v[74:75], v[56:59], off offset:64
	v_add_u32_e32 v50, 0xa0, v182
	s_and_b64 vcc, exec, s[44:45]
	v_ashrrev_i32_e32 v51, 31, v50
	s_cbranch_vccnz .LBB0_488
	v_lshlrev_b64 v[52:53], 7, v[50:51]
	v_readlane_b32 s18, v254, 8
	v_readlane_b32 s20, v254, 10
	v_or_b32_e32 v52, v52, v0
	v_readlane_b32 s19, v254, 9
	v_readlane_b32 s21, v254, 11
	v_or_b32_e32 v62, v62, v0
	v_lshl_add_u64 v[54:55], s[18:19], 0, v[52:53]
	v_lshl_add_u64 v[52:53], s[20:21], 0, v[52:53]
	s_mov_b64 s[28:29], 0x5800
	v_lshl_add_u64 v[52:53], v[62:63], 0, s[28:29]
	v_lshl_add_u64 v[54:55], s[18:19], 0, v[52:53]
	v_lshl_add_u64 v[52:53], s[20:21], 0, v[52:53]
	ds_read_b128 v[98:101], v250 offset:9232
	ds_read_b128 v[126:129], v250 offset:9216
	ds_read_b128 v[122:125], v250 offset:23056
	ds_read_b128 v[138:141], v250 offset:23040
	ds_read_b128 v[66:69], v250 offset:11536
	ds_read_b128 v[86:89], v250 offset:11520
	ds_read_b128 v[78:81], v250 offset:25360
	ds_read_b128 v[94:97], v250 offset:25344
;   DI void operator()(LAS unsigned char* lds, f32x4 (&acc)[2][2][4][2], int pm, int pn, int wr, int wc, int fr, int fq) const {
;     ...
;       for (int m = mb; m < mb + 2; ++m) {
;         const int s = s0 + ai * HALF + m * 16;
;         f32x4 v[2][2];
; #pragma unroll
;         for (int bj = 0; bj < 2; ++bj)
; #pragma unroll
;           for (int n = 0; n < 2; ++n) v[bj][n] = acc[ai][bj][m][n] * rstd[ai][m];
;         if (type < 2) {
;           float q = 0.f;
; #pragma unroll
;           for (int bj = 0; bj < 2; ++bj)
; #pragma unroll
;             for (int n = 0; n < 2; ++n) q += v[bj][n][0] * v[bj][n][0] + v[bj][n][1] * v[bj][n][1] + v[bj][n][2] * v[bj][n][2] + v[bj][n][3] * v[bj][n][3];
;           q += __shfl_xor(q, 16); q += __shfl_xor(q, 32);
;           float rn = rsqrtf(q * (1.0f / 64.0f) + EPS);
;           if (type == 0) rn *= 0.125f * LOG2E;
; #pragma unroll
;           for (int n = 0; n < 2; ++n) {
;             const f32x4 x1 = v[0][n] * g1[n] * rn, x2 = v[1][n] * g2[n] * rn;
;             v[0][n] = x1 * cs[m][n] - x2 * sn[m][n]; v[1][n] = x2 * cs[m][n] + x1 * sn[m][n];
;           }
.LBB0_488:
	v_pk_mul_f32 v[44:45], v[44:45], v[178:179] op_sel_hi:[1,0]
	v_pk_mul_f32 v[42:43], v[42:43], v[178:179] op_sel_hi:[1,0]
	v_pk_mul_f32 v[40:41], v[40:41], v[178:179] op_sel_hi:[1,0]
	v_pk_mul_f32 v[52:53], v[38:39], v[178:179] op_sel_hi:[1,0]
	v_pk_mul_f32 v[38:39], v[48:49], v[178:179] op_sel_hi:[1,0]
	v_pk_mul_f32 v[46:47], v[46:47], v[178:179] op_sel_hi:[1,0]
	v_pk_mul_f32 v[36:37], v[36:37], v[178:179] op_sel_hi:[1,0]
	s_and_b64 vcc, exec, s[44:45]
	v_pk_mul_f32 v[34:35], v[34:35], v[178:179] op_sel_hi:[1,0]
	s_cbranch_vccnz .LBB0_490
	v_mov_b32_e32 v54, v43
	v_mov_b32_e32 v55, v53
	v_mov_b32_e32 v48, v42
	v_mov_b32_e32 v49, v52
	v_pk_mul_f32 v[54:55], v[54:55], v[54:55]
	v_mov_b32_e32 v56, v35
	v_pk_fma_f32 v[48:49], v[48:49], v[48:49], v[54:55]
	v_mov_b32_e32 v54, v44
	v_mov_b32_e32 v55, v40
	v_pk_fma_f32 v[48:49], v[54:55], v[54:55], v[48:49]
	v_mov_b32_e32 v54, v45
	v_mov_b32_e32 v55, v41
	v_mov_b32_e32 v57, v47
	v_pk_fma_f32 v[48:49], v[54:55], v[54:55], v[48:49]
	v_mov_b32_e32 v54, v34
	v_mov_b32_e32 v55, v46
	v_pk_mul_f32 v[56:57], v[56:57], v[56:57]
	v_add_f32_e32 v0, v48, v49
	v_pk_fma_f32 v[54:55], v[54:55], v[54:55], v[56:57]
	v_mov_b32_e32 v56, v36
	v_mov_b32_e32 v57, v38
	v_and_b32_e32 v49, 64, v224
	v_pk_fma_f32 v[54:55], v[56:57], v[56:57], v[54:55]
	v_mov_b32_e32 v56, v37
	v_mov_b32_e32 v57, v39
	v_xor_b32_e32 v48, 16, v224
	v_add_u32_e32 v49, 64, v49
	v_pk_fma_f32 v[54:55], v[56:57], v[56:57], v[54:55]
	v_cmp_lt_i32_e32 vcc, v48, v49
	v_add_f32_e32 v0, v55, v0
	v_add_f32_e32 v0, v54, v0
	v_cndmask_b32_e32 v48, v224, v48, vcc
	v_lshlrev_b32_e32 v48, 2, v48
	ds_bpermute_b32 v48, v48, v0
	v_pk_mul_f32 v[42:43], v[42:43], v[14:15]
	v_pk_mul_f32 v[38:39], v[38:39], v[12:13]
	v_pk_mul_f32 v[44:45], v[44:45], v[16:17]
	v_pk_mul_f32 v[36:37], v[36:37], v[4:5]
	s_waitcnt lgkmcnt(0)
	v_add_f32_e32 v0, v0, v48
	v_xor_b32_e32 v48, 32, v224
	v_cmp_lt_i32_e32 vcc, v48, v49
	v_pk_mul_f32 v[34:35], v[34:35], v[2:3]
	v_pk_mul_f32 v[40:41], v[40:41], v[8:9]
	v_cndmask_b32_e32 v48, v224, v48, vcc
	v_lshlrev_b32_e32 v48, 2, v48
	ds_bpermute_b32 v48, v48, v0
	s_waitcnt lgkmcnt(0)
	v_add_f32_e32 v0, v0, v48
	v_fmamk_f32 v0, v0, 0x3c800000, v227
	v_mul_f32_e32 v48, 0x4b800000, v0
	v_cmp_gt_f32_e32 vcc, s16, v0
	s_nop 1
	v_cndmask_b32_e32 v0, v0, v48, vcc
	v_rsq_f32_e32 v0, v0
	s_nop 0
	v_mul_f32_e32 v48, 0x45800000, v0
	v_cndmask_b32_e32 v0, v0, v48, vcc
	v_mul_f32_e32 v48, 0x3e38aa3b, v0
	v_cndmask_b32_e64 v0, v0, v48, s[96:97]
	v_pk_mul_f32 v[48:49], v[42:43], v[0:1] op_sel_hi:[1,0]
	v_pk_mul_f32 v[42:43], v[46:47], v[10:11]
	v_pk_mul_f32 v[38:39], v[38:39], v[0:1] op_sel_hi:[1,0]
	v_pk_mul_f32 v[46:47], v[42:43], v[0:1] op_sel_hi:[1,0]
	v_pk_mul_f32 v[54:55], v[44:45], v[0:1] op_sel_hi:[1,0]
	s_waitcnt lgkmcnt(0)
	v_pk_mul_f32 v[42:43], v[138:139], v[46:47]
	v_pk_mul_f32 v[44:45], v[140:141], v[38:39]
	v_pk_fma_f32 v[42:43], v[126:127], v[48:49], v[42:43] neg_lo:[0,0,1] neg_hi:[0,0,1]
	v_pk_mul_f32 v[48:49], v[138:139], v[48:49]
	v_pk_fma_f32 v[44:45], v[128:129], v[54:55], v[44:45] neg_lo:[0,0,1] neg_hi:[0,0,1]
	v_pk_mul_f32 v[54:55], v[140:141], v[54:55]
	v_pk_fma_f32 v[46:47], v[126:127], v[46:47], v[48:49]
	v_pk_mul_f32 v[48:49], v[52:53], v[6:7]
	v_pk_mul_f32 v[36:37], v[36:37], v[0:1] op_sel_hi:[1,0]
	v_pk_mul_f32 v[34:35], v[34:35], v[0:1] op_sel_hi:[1,0]
	v_pk_fma_f32 v[38:39], v[128:129], v[38:39], v[54:55]
	v_pk_mul_f32 v[48:49], v[48:49], v[0:1] op_sel_hi:[1,0]
	v_pk_mul_f32 v[54:55], v[40:41], v[0:1] op_sel_hi:[1,0]
	v_pk_mul_f32 v[52:53], v[122:123], v[34:35]
	v_pk_mul_f32 v[40:41], v[124:125], v[36:37]
	v_pk_fma_f32 v[52:53], v[98:99], v[48:49], v[52:53] neg_lo:[0,0,1] neg_hi:[0,0,1]
	v_pk_fma_f32 v[40:41], v[100:101], v[54:55], v[40:41] neg_lo:[0,0,1] neg_hi:[0,0,1]
	v_pk_mul_f32 v[48:49], v[122:123], v[48:49]
	v_pk_mul_f32 v[54:55], v[124:125], v[54:55]
	v_pk_fma_f32 v[34:35], v[98:99], v[34:35], v[48:49]
	v_pk_fma_f32 v[36:37], v[100:101], v[36:37], v[54:55]
; DI unsigned cvt_pk(float lo, float hi) { unsigned r; asm("v_cvt_pk_bf16_f32 %0, %1, %2" : "=v"(r) : "v"(lo), "v"(hi)); return r; }
;   DI void operator()(LAS unsigned char* lds, f32x4 (&acc)[2][2][4][2], int pm, int pn, int wr, int wc, int fr, int fq) const {
;     ...
;       for (int m = mb; m < mb + 2; ++m) {
;         const int s = s0 + ai * HALF + m * 16;
;         f32x4 v[2][2];
; #pragma unroll
;         for (int bj = 0; bj < 2; ++bj)
; #pragma unroll
;           for (int n = 0; n < 2; ++n) v[bj][n] = acc[ai][bj][m][n] * rstd[ai][m];
;         if (type < 2) {
;           float q = 0.f;
; #pragma unroll
;           for (int bj = 0; bj < 2; ++bj)
; #pragma unroll
;             for (int n = 0; n < 2; ++n) q += v[bj][n][0] * v[bj][n][0] + v[bj][n][1] * v[bj][n][1] + v[bj][n][2] * v[bj][n][2] + v[bj][n][3] * v[bj][n][3];
;           q += __shfl_xor(q, 16); q += __shfl_xor(q, 32);
;           float rn = rsqrtf(q * (1.0f / 64.0f) + EPS);
;           if (type == 0) rn *= 0.125f * LOG2E;
; #pragma unroll
;           for (int n = 0; n < 2; ++n) {
;             const f32x4 x1 = v[0][n] * g1[n] * rn, x2 = v[1][n] * g2[n] * rn;
;             v[0][n] = x1 * cs[m][n] - x2 * sn[m][n]; v[1][n] = x2 * cs[m][n] + x1 * sn[m][n];
;           }
;         }
;         bf16_t* rp = base + (size_t)s * 64 + 8 * fq;
; #pragma unroll
;         for (int bj = 0; bj < 2; ++bj) {
;           u32x4 w; w.x = cvt_pk(v[bj][0][0], v[bj][0][1]); w.y = cvt_pk(v[bj][0][2], v[bj][0][3]); w.z = cvt_pk(v[bj][1][0], v[bj][1][1]); w.w = cvt_pk(v[bj][1][2], v[bj][1][3]);
;           *(u32x4*)(rp + bj * 32) = w;
;         }
.LBB0_490:
	v_lshlrev_b64 v[48:49], 7, v[50:51]
	v_lshl_add_u64 v[48:49], v[180:181], 0, v[48:49]
	v_cvt_pk_bf16_f32 v42, v42, v43
	v_cvt_pk_bf16_f32 v43, v44, v45
	v_mov_b32_e32 v0, v179
	v_cvt_pk_bf16_f32 v44, v52, v53
	v_cvt_pk_bf16_f32 v45, v40, v41
	global_store_dwordx4 v[48:49], v[42:45], off
	v_pk_mul_f32 v[28:29], v[28:29], v[0:1] op_sel_hi:[1,0]
	v_pk_mul_f32 v[20:21], v[20:21], v[0:1] op_sel_hi:[1,0]
	v_cvt_pk_bf16_f32 v42, v34, v35
	v_cvt_pk_bf16_f32 v43, v36, v37
	v_pk_mul_f32 v[34:35], v[26:27], v[0:1] op_sel_hi:[1,0]
	v_pk_mul_f32 v[26:27], v[24:25], v[0:1] op_sel_hi:[1,0]
	v_pk_mul_f32 v[36:37], v[22:23], v[0:1] op_sel_hi:[1,0]
	v_pk_mul_f32 v[22:23], v[32:33], v[0:1] op_sel_hi:[1,0]
	v_pk_mul_f32 v[24:25], v[30:31], v[0:1] op_sel_hi:[1,0]
	s_and_b64 vcc, exec, s[44:45]
	v_pk_mul_f32 v[18:19], v[18:19], v[0:1] op_sel_hi:[1,0]
	v_cvt_pk_bf16_f32 v40, v46, v47
	v_cvt_pk_bf16_f32 v41, v38, v39
	global_store_dwordx4 v[48:49], v[40:43], off offset:64
	s_cbranch_vccnz .LBB0_447
	v_mov_b32_e32 v32, v35
	v_mov_b32_e32 v33, v37
	v_mov_b32_e32 v30, v34
	v_mov_b32_e32 v31, v36
	v_pk_mul_f32 v[32:33], v[32:33], v[32:33]
	v_mov_b32_e32 v38, v19
	v_pk_fma_f32 v[30:31], v[30:31], v[30:31], v[32:33]
	v_mov_b32_e32 v32, v28
	v_mov_b32_e32 v33, v26
	v_pk_fma_f32 v[30:31], v[32:33], v[32:33], v[30:31]
	v_mov_b32_e32 v32, v29
	v_mov_b32_e32 v33, v27
	v_mov_b32_e32 v39, v25
	v_pk_fma_f32 v[30:31], v[32:33], v[32:33], v[30:31]
	v_mov_b32_e32 v32, v18
	v_mov_b32_e32 v33, v24
	v_pk_mul_f32 v[38:39], v[38:39], v[38:39]
	v_add_f32_e32 v0, v30, v31
	v_pk_fma_f32 v[32:33], v[32:33], v[32:33], v[38:39]
	v_mov_b32_e32 v38, v20
	v_mov_b32_e32 v39, v22
	v_and_b32_e32 v31, 64, v224
	v_pk_fma_f32 v[32:33], v[38:39], v[38:39], v[32:33]
	v_mov_b32_e32 v38, v21
	v_mov_b32_e32 v39, v23
	v_xor_b32_e32 v30, 16, v224
	v_add_u32_e32 v31, 64, v31
	v_pk_fma_f32 v[32:33], v[38:39], v[38:39], v[32:33]
	v_cmp_lt_i32_e32 vcc, v30, v31
	v_add_f32_e32 v0, v33, v0
	v_add_f32_e32 v0, v32, v0
	v_cndmask_b32_e32 v30, v224, v30, vcc
	v_lshlrev_b32_e32 v30, 2, v30
	ds_bpermute_b32 v30, v30, v0
	v_pk_mul_f32 v[12:13], v[22:23], v[12:13]
	v_pk_mul_f32 v[10:11], v[24:25], v[10:11]
	v_pk_mul_f32 v[16:17], v[28:29], v[16:17]
	v_pk_mul_f32 v[14:15], v[34:35], v[14:15]
	s_waitcnt lgkmcnt(0)
	v_add_f32_e32 v0, v0, v30
	v_xor_b32_e32 v30, 32, v224
	v_cmp_lt_i32_e32 vcc, v30, v31
	v_pk_mul_f32 v[4:5], v[20:21], v[4:5]
	v_pk_mul_f32 v[2:3], v[18:19], v[2:3]
	v_cndmask_b32_e32 v30, v224, v30, vcc
	v_lshlrev_b32_e32 v30, 2, v30
	ds_bpermute_b32 v30, v30, v0
	v_pk_mul_f32 v[8:9], v[26:27], v[8:9]
	v_pk_mul_f32 v[6:7], v[36:37], v[6:7]
	s_waitcnt lgkmcnt(0)
	v_add_f32_e32 v0, v0, v30
	v_fmamk_f32 v0, v0, 0x3c800000, v227
	v_mul_f32_e32 v30, 0x4b800000, v0
	v_cmp_gt_f32_e32 vcc, s16, v0
	s_nop 1
	v_cndmask_b32_e32 v0, v0, v30, vcc
	v_rsq_f32_e32 v0, v0
	s_nop 0
	v_mul_f32_e32 v30, 0x45800000, v0
	v_cndmask_b32_e32 v0, v0, v30, vcc
	v_mul_f32_e32 v30, 0x3e38aa3b, v0
	v_cndmask_b32_e64 v0, v0, v30, s[96:97]
	v_pk_mul_f32 v[12:13], v[12:13], v[0:1] op_sel_hi:[1,0]
	v_pk_mul_f32 v[10:11], v[10:11], v[0:1] op_sel_hi:[1,0]
	v_pk_mul_f32 v[14:15], v[14:15], v[0:1] op_sel_hi:[1,0]
	v_pk_mul_f32 v[16:17], v[16:17], v[0:1] op_sel_hi:[1,0]
	s_waitcnt lgkmcnt(0)
	v_pk_mul_f32 v[22:23], v[94:95], v[10:11]
	v_pk_mul_f32 v[24:25], v[96:97], v[12:13]
	v_pk_fma_f32 v[34:35], v[86:87], v[14:15], v[22:23] neg_lo:[0,0,1] neg_hi:[0,0,1]
	v_pk_fma_f32 v[28:29], v[88:89], v[16:17], v[24:25] neg_lo:[0,0,1] neg_hi:[0,0,1]
	v_pk_mul_f32 v[14:15], v[94:95], v[14:15]
	v_pk_mul_f32 v[16:17], v[96:97], v[16:17]
	v_pk_mul_f32 v[4:5], v[4:5], v[0:1] op_sel_hi:[1,0]
	v_pk_mul_f32 v[2:3], v[2:3], v[0:1] op_sel_hi:[1,0]
	v_pk_fma_f32 v[22:23], v[88:89], v[12:13], v[16:17]
	v_pk_fma_f32 v[24:25], v[86:87], v[10:11], v[14:15]
	v_pk_mul_f32 v[6:7], v[6:7], v[0:1] op_sel_hi:[1,0]
	v_pk_mul_f32 v[8:9], v[8:9], v[0:1] op_sel_hi:[1,0]
	v_pk_mul_f32 v[10:11], v[78:79], v[2:3]
	v_pk_mul_f32 v[12:13], v[80:81], v[4:5]
	v_pk_fma_f32 v[36:37], v[66:67], v[6:7], v[10:11] neg_lo:[0,0,1] neg_hi:[0,0,1]
	v_pk_fma_f32 v[26:27], v[68:69], v[8:9], v[12:13] neg_lo:[0,0,1] neg_hi:[0,0,1]
	v_pk_mul_f32 v[6:7], v[78:79], v[6:7]
	v_pk_mul_f32 v[8:9], v[80:81], v[8:9]
	v_pk_fma_f32 v[18:19], v[66:67], v[2:3], v[6:7]
	v_pk_fma_f32 v[20:21], v[68:69], v[4:5], v[8:9]
	s_branch .LBB0_447
